# v79: mLSTM output pass: the 32 weight / output-gate loads of a unit's epilogue issued together instead of one serialized round trip per column group
# speedup vs baseline: 1.0080x; 1.0048x over previous
.LBB0_9:
	s_mul_i32 s3, s6, 3
	s_getpc_b64 s[0:1]
	s_add_u32 s0, s0, PROG@rel32@lo+4
	s_addc_u32 s1, s1, PROG@rel32@hi+12
	s_and_b32 s2, s3, -4
	s_add_u32 s0, s0, s2
	s_addc_u32 s1, s1, 0
	s_load_dwordx2 s[0:1], s[0:1], 0x0
	s_and_b32 s3, s3, 3
	s_lshl_b32 s3, s3, 3
	s_waitcnt lgkmcnt(0)
	s_lshr_b64 s[0:1], s[0:1], s3
	s_and_b32 s2, s0, 0xffff
	v_mov_b32_e32 v0, s2
	s_bfe_u32 s2, s0, 0x80010
	v_mov_b32_e32 v2, s2
	s_cmp_gt_u32 s6, 1
	s_cbranch_scc1 .Lsm_done
	v_readlane_b32 s0, v254, 39
	v_readlane_b32 s1, v254, 40
	s_add_u32 s0, s0, 0xc000
	s_addc_u32 s1, s1, 0
	s_cmp_eq_u32 s6, 1
	s_cbranch_scc1 .Lsm_cache
	s_getreg_b32 s2, hwreg(HW_REG_XCC_ID, 0, 4)
	s_and_b32 s2, s2, 15
	s_lshl_b32 s2, 1, s2
	s_and_b32 s3, s66, 7
	s_lshl_b32 s3, s3, 2
	s_add_u32 s0, s0, s3
	s_addc_u32 s1, s1, 0
	v_mov_b32_e32 v3, s2
	s_mov_b64 s[2:3], exec
	s_mov_b64 exec, 1
	global_atomic_or v1, v3, s[0:1]
	s_mov_b64 exec, s[2:3]
	s_branch .Lsm_done
	s_nop 0
	s_nop 0
	s_nop 0
	s_nop 0
	s_nop 0
.Lsm_cache:
	global_load_dwordx4 v[4:7], v1, s[0:1] sc1
	global_load_dwordx4 v[8:11], v1, s[0:1] offset:16 sc1
	s_waitcnt vmcnt(0)
	v_add_u32_e32 v3, -1, v4
	v_and_b32_e32 v3, v3, v4
	v_add_u32_e32 v4, -1, v5
	v_and_or_b32 v3, v4, v5, v3
	v_add_u32_e32 v4, -1, v6
	v_and_or_b32 v3, v4, v6, v3
	v_add_u32_e32 v4, -1, v7
	v_and_or_b32 v3, v4, v7, v3
	v_add_u32_e32 v4, -1, v8
	v_and_or_b32 v3, v4, v8, v3
	v_add_u32_e32 v4, -1, v9
	v_and_or_b32 v3, v4, v9, v3
	v_add_u32_e32 v4, -1, v10
	v_and_or_b32 v3, v4, v10, v3
	v_add_u32_e32 v4, -1, v11
	v_and_or_b32 v3, v4, v11, v3
	s_nop 0
	v_readfirstlane_b32 s2, v3
	s_nop 1
	v_writelane_b32 v255, s2, 63

.LBB0_170:
	v_pk_mul_f32 v[66:67], v[64:65], v[64:65]
	v_pk_mul_f32 v[68:69], v[62:63], v[62:63]
	v_mul_f32_e32 v0, v50, v50
	v_pk_mov_b32 v[70:71], v[68:69], v[66:67] op_sel:[1,0]
	v_mov_b32_e32 v69, v67
	v_pk_add_f32 v[66:67], v[70:71], v[68:69]
	v_pk_mul_f32 v[68:69], v[60:61], v[60:61]
	v_pk_mul_f32 v[70:71], v[58:59], v[58:59]
	v_pk_add_f32 v[66:67], v[66:67], v[66:67] op_sel:[0,1] op_sel_hi:[1,0]
	v_pk_mov_b32 v[72:73], v[70:71], v[68:69] op_sel:[1,0]
	v_mov_b32_e32 v71, v69
	v_pk_add_f32 v[68:69], v[72:73], v[70:71]
	v_mul_f32_e32 v70, v51, v51
	v_pk_add_f32 v[68:69], v[68:69], v[68:69] op_sel:[0,1] op_sel_hi:[1,0]
	v_mov_b32_e32 v67, v0
	v_mov_b32_e32 v69, v70
	v_mul_f32_e32 v0, v55, v55
	v_mul_f32_e32 v71, v52, v52
	v_pk_add_f32 v[66:67], v[66:67], v[68:69]
	v_pk_fma_f32 v[68:69], v[54:55], v[54:55], v[0:1] op_sel_hi:[1,1,0]
	v_mul_f32_e32 v0, v57, v57
	v_mul_f32_e32 v72, v53, v53
	v_mov_b32_e32 v69, v71
	v_pk_fma_f32 v[70:71], v[56:57], v[56:57], v[0:1] op_sel_hi:[1,1,0]
	v_mul_f32_e32 v0, v38, v38
	v_mov_b32_e32 v71, v72
	v_pk_add_f32 v[68:69], v[68:69], v[70:71]
	v_pk_mul_f32 v[70:71], v[46:47], v[46:47]
	v_pk_add_f32 v[66:67], v[66:67], v[68:69]
	v_pk_mul_f32 v[68:69], v[48:49], v[48:49]
	v_pk_add_f32 v[66:67], v[66:67], v[66:67] op_sel:[0,1] op_sel_hi:[1,0]
	v_pk_mov_b32 v[72:73], v[70:71], v[68:69] op_sel:[1,0]
	v_mov_b32_e32 v71, v69
	v_pk_add_f32 v[68:69], v[72:73], v[70:71]
	v_mul_f32_e32 v70, v39, v39
	v_pk_add_f32 v[68:69], v[68:69], v[68:69] op_sel:[0,1] op_sel_hi:[1,0]
	v_mov_b32_e32 v67, v0
	v_mov_b32_e32 v69, v70
	v_mul_f32_e32 v0, v43, v43
	v_mul_f32_e32 v71, v40, v40
	v_pk_add_f32 v[66:67], v[66:67], v[68:69]
	v_pk_fma_f32 v[68:69], v[42:43], v[42:43], v[0:1] op_sel_hi:[1,1,0]
	v_mul_f32_e32 v0, v45, v45
	v_mul_f32_e32 v72, v41, v41
	v_mov_b32_e32 v69, v71
	v_pk_fma_f32 v[70:71], v[44:45], v[44:45], v[0:1] op_sel_hi:[1,1,0]
	v_mul_f32_e32 v0, v26, v26
	v_mov_b32_e32 v71, v72
	v_pk_add_f32 v[68:69], v[68:69], v[70:71]
	v_pk_mul_f32 v[70:71], v[34:35], v[34:35]
	v_pk_add_f32 v[66:67], v[66:67], v[68:69]
	v_pk_mul_f32 v[68:69], v[36:37], v[36:37]
	v_pk_add_f32 v[66:67], v[66:67], v[66:67] op_sel:[0,1] op_sel_hi:[1,0]
	v_pk_mov_b32 v[72:73], v[70:71], v[68:69] op_sel:[1,0]
	v_mov_b32_e32 v71, v69
	v_pk_add_f32 v[68:69], v[72:73], v[70:71]
	v_mul_f32_e32 v70, v27, v27
	v_pk_add_f32 v[68:69], v[68:69], v[68:69] op_sel:[0,1] op_sel_hi:[1,0]
	v_mov_b32_e32 v67, v0
	v_mov_b32_e32 v69, v70
	v_mul_f32_e32 v0, v31, v31
	v_mul_f32_e32 v71, v28, v28
	v_pk_add_f32 v[66:67], v[66:67], v[68:69]
	v_pk_fma_f32 v[68:69], v[30:31], v[30:31], v[0:1] op_sel_hi:[1,1,0]
	v_mul_f32_e32 v0, v33, v33
	v_mul_f32_e32 v72, v29, v29
	v_mov_b32_e32 v69, v71
	v_pk_fma_f32 v[70:71], v[32:33], v[32:33], v[0:1] op_sel_hi:[1,1,0]
	v_mul_f32_e32 v0, v14, v14
	v_mov_b32_e32 v71, v72
	v_pk_add_f32 v[68:69], v[68:69], v[70:71]
	v_pk_mul_f32 v[70:71], v[22:23], v[22:23]
	v_pk_add_f32 v[66:67], v[66:67], v[68:69]
	v_pk_mul_f32 v[68:69], v[24:25], v[24:25]
	v_pk_add_f32 v[66:67], v[66:67], v[66:67] op_sel:[0,1] op_sel_hi:[1,0]
	v_pk_mov_b32 v[72:73], v[70:71], v[68:69] op_sel:[1,0]
	v_mov_b32_e32 v71, v69
	v_pk_add_f32 v[68:69], v[72:73], v[70:71]
	v_mul_f32_e32 v70, v15, v15
	v_pk_add_f32 v[68:69], v[68:69], v[68:69] op_sel:[0,1] op_sel_hi:[1,0]
	v_mov_b32_e32 v67, v0
	v_mov_b32_e32 v69, v70
	v_mul_f32_e32 v0, v19, v19
	v_mul_f32_e32 v71, v16, v16
	v_pk_add_f32 v[66:67], v[66:67], v[68:69]
	v_pk_fma_f32 v[68:69], v[18:19], v[18:19], v[0:1] op_sel_hi:[1,1,0]
	v_mul_f32_e32 v0, v21, v21
	v_mul_f32_e32 v72, v17, v17
	v_mov_b32_e32 v69, v71
	v_pk_fma_f32 v[70:71], v[20:21], v[20:21], v[0:1] op_sel_hi:[1,1,0]
	v_mul_f32_e32 v0, v2, v2
	v_mov_b32_e32 v71, v72
	v_pk_add_f32 v[68:69], v[68:69], v[70:71]
	v_pk_mul_f32 v[70:71], v[10:11], v[10:11]
	v_pk_add_f32 v[66:67], v[66:67], v[68:69]
	v_pk_mul_f32 v[68:69], v[12:13], v[12:13]
	v_pk_add_f32 v[66:67], v[66:67], v[66:67] op_sel:[0,1] op_sel_hi:[1,0]
	v_pk_mov_b32 v[72:73], v[70:71], v[68:69] op_sel:[1,0]
	v_mov_b32_e32 v71, v69
	v_pk_add_f32 v[68:69], v[72:73], v[70:71]
	v_mul_f32_e32 v70, v3, v3
	v_pk_add_f32 v[68:69], v[68:69], v[68:69] op_sel:[0,1] op_sel_hi:[1,0]
	v_mov_b32_e32 v67, v0
	v_mov_b32_e32 v69, v70
	v_mul_f32_e32 v0, v7, v7
	v_mul_f32_e32 v71, v4, v4
	v_pk_add_f32 v[66:67], v[66:67], v[68:69]
	v_pk_fma_f32 v[68:69], v[6:7], v[6:7], v[0:1] op_sel_hi:[1,1,0]
	v_mul_f32_e32 v0, v9, v9
	v_mul_f32_e32 v72, v5, v5
	v_mov_b32_e32 v69, v71
	v_pk_fma_f32 v[70:71], v[8:9], v[8:9], v[0:1] op_sel_hi:[1,1,0]
	v_readlane_b32 s2, v255, 14
	v_mov_b32_e32 v71, v72
	v_pk_add_f32 v[68:69], v[68:69], v[70:71]
	v_readlane_b32 s3, v255, 15
	v_pk_add_f32 v[66:67], v[66:67], v[68:69]
	s_load_dwordx2 s[2:3], s[2:3], 0xa0
	v_add_f32_e32 v0, v66, v67
	ds_bpermute_b32 v66, v171, v0
	s_add_i32 s6, s38, s0
	s_waitcnt lgkmcnt(0)
	v_add_f32_e32 v0, v0, v66
	ds_bpermute_b32 v66, v170, v0
	s_waitcnt lgkmcnt(0)
	v_add_f32_e32 v0, v0, v66
	v_fmamk_f32 v0, v0, 0x3b800000, v167
	v_mul_f32_e32 v66, 0x4b800000, v0
	v_cmp_gt_f32_e32 vcc, s33, v0
	s_nop 1
	v_cndmask_b32_e32 v0, v0, v66, vcc
	v_rsq_f32_e32 v0, v0
	s_nop 0
	v_mul_f32_e32 v66, 0x45800000, v0
	v_cndmask_b32_e32 v0, v0, v66, vcc
	v_or_b32_e32 v66, s6, v131
	v_ashrrev_i32_e32 v67, 31, v66
	s_lshl_b32 s6, s73, 2
	s_add_u32 s2, s2, s6
	v_lshlrev_b64 v[66:67], 11, v[66:67]
	v_readlane_b32 s6, v255, 40
	v_lshl_or_b32 v66, s73, 1, v66
	v_readlane_b32 s7, v255, 41
	s_addc_u32 s3, s3, 0
	s_nop 0
	v_lshl_add_u64 v[74:75], s[6:7], 0, v[66:67]
	v_readlane_b32 s6, v255, 9
	v_readlane_b32 s7, v255, 10
	s_nop 1
	v_lshl_add_u64 v[76:77], s[6:7], 0, v[66:67]
	v_ashrrev_i32_e32 v131, 31, v130
	v_lshlrev_b64 v[78:79], 1, v[130:131]
	v_lshl_add_u64 v[68:69], v[130:131], 2, s[2:3]
	v_lshl_add_u64 v[66:67], v[74:75], 0, v[78:79]
	global_load_dwordx4 v[132:135], v[68:69], off
	global_load_dwordx2 v[82:83], v[66:67], off
	global_load_dwordx4 v[136:139], v[68:69], off offset:64
	global_load_dwordx2 v[84:85], v[66:67], off offset:32
	global_load_dwordx4 v[140:143], v[68:69], off offset:128
	global_load_dwordx2 v[86:87], v[66:67], off offset:64
	global_load_dwordx4 v[144:147], v[68:69], off offset:192
	global_load_dwordx2 v[88:89], v[66:67], off offset:96
	global_load_dwordx4 v[148:151], v[68:69], off offset:256
	global_load_dwordx2 v[90:91], v[66:67], off offset:128
	global_load_dwordx4 v[152:155], v[68:69], off offset:320
	global_load_dwordx2 v[92:93], v[66:67], off offset:160
	global_load_dwordx4 v[156:159], v[68:69], off offset:384
	global_load_dwordx2 v[94:95], v[66:67], off offset:192
	global_load_dwordx4 v[160:163], v[68:69], off offset:448
	global_load_dwordx2 v[96:97], v[66:67], off offset:224
	global_load_dwordx4 v[172:175], v[68:69], off offset:512
	global_load_dwordx2 v[102:103], v[66:67], off offset:256
	global_load_dwordx4 v[176:179], v[68:69], off offset:576
	global_load_dwordx2 v[104:105], v[66:67], off offset:288
	global_load_dwordx4 v[180:183], v[68:69], off offset:640
	global_load_dwordx2 v[106:107], v[66:67], off offset:320
	global_load_dwordx4 v[184:187], v[68:69], off offset:704
	global_load_dwordx2 v[108:109], v[66:67], off offset:352
	global_load_dwordx4 v[188:191], v[68:69], off offset:768
	global_load_dwordx2 v[110:111], v[66:67], off offset:384
	global_load_dwordx4 v[192:195], v[68:69], off offset:832
	global_load_dwordx2 v[112:113], v[66:67], off offset:416
	global_load_dwordx4 v[196:199], v[68:69], off offset:896
	global_load_dwordx2 v[120:121], v[66:67], off offset:448
	global_load_dwordx4 v[204:207], v[68:69], off offset:960
	global_load_dwordx2 v[122:123], v[66:67], off offset:480
	s_waitcnt vmcnt(0)
	v_mov_b32_e32 v70, v132
	v_mov_b32_e32 v71, v133
	v_mov_b32_e32 v72, v134
	v_mov_b32_e32 v73, v135
	v_mov_b32_e32 v74, v82
	v_mov_b32_e32 v75, v83
	v_pk_mul_f32 v[80:81], v[62:63], v[0:1] op_sel_hi:[1,0]
	v_pk_mul_f32 v[64:65], v[64:65], v[0:1] op_sel_hi:[1,0]
	v_lshl_add_u64 v[62:63], v[76:77], 0, v[78:79]
	v_mov_b32_e32 v76, v84
	v_mov_b32_e32 v77, v85
	v_pk_mul_f32 v[58:59], v[58:59], v[0:1] op_sel_hi:[1,0]
	v_pk_mul_f32 v[60:61], v[60:61], v[0:1] op_sel_hi:[1,0]
	v_pk_mul_f32 v[54:55], v[54:55], v[0:1] op_sel_hi:[1,0]
	v_pk_mul_f32 v[56:57], v[56:57], v[0:1] op_sel_hi:[1,0]
	v_pk_mul_f32 v[50:51], v[50:51], v[0:1] op_sel_hi:[1,0]
	v_pk_mul_f32 v[52:53], v[52:53], v[0:1] op_sel_hi:[1,0]
	v_pk_mul_f32 v[70:71], v[70:71], v[80:81]
	v_pk_mul_f32 v[64:65], v[72:73], v[64:65]
	v_lshlrev_b32_e32 v72, 16, v74
	v_and_b32_e32 v73, 0xffff0000, v74
	v_lshlrev_b32_e32 v74, 16, v75
	v_and_b32_e32 v75, 0xffff0000, v75
	v_pk_mul_f32 v[70:71], v[70:71], v[72:73]
	v_pk_mul_f32 v[64:65], v[64:65], v[74:75]
	v_cvt_pk_bf16_f32 v70, v70, v71
	v_cvt_pk_bf16_f32 v71, v64, v65
	global_store_dwordx2 v[62:63], v[70:71], off
	v_mov_b32_e32 v70, v136
	v_mov_b32_e32 v71, v137
	v_mov_b32_e32 v72, v138
	v_mov_b32_e32 v73, v139
	v_lshlrev_b32_e32 v74, 16, v76
	v_and_b32_e32 v75, 0xffff0000, v76
	v_lshlrev_b32_e32 v76, 16, v77
	v_and_b32_e32 v77, 0xffff0000, v77
	v_mov_b32_e32 v64, v86
	v_mov_b32_e32 v65, v87
	v_pk_mul_f32 v[58:59], v[70:71], v[58:59]
	v_pk_mul_f32 v[60:61], v[72:73], v[60:61]
	v_pk_mul_f32 v[58:59], v[58:59], v[74:75]
	v_pk_mul_f32 v[60:61], v[60:61], v[76:77]
	v_cvt_pk_bf16_f32 v58, v58, v59
	v_cvt_pk_bf16_f32 v59, v60, v61
	global_store_dwordx2 v[62:63], v[58:59], off offset:32
	v_mov_b32_e32 v58, v140
	v_mov_b32_e32 v59, v141
	v_mov_b32_e32 v60, v142
	v_mov_b32_e32 v61, v143
	v_pk_mul_f32 v[54:55], v[58:59], v[54:55]
	v_mov_b32_e32 v70, v88
	v_mov_b32_e32 v71, v89
	v_lshlrev_b32_e32 v72, 16, v64
	v_and_b32_e32 v73, 0xffff0000, v64
	v_lshlrev_b32_e32 v64, 16, v65
	v_and_b32_e32 v65, 0xffff0000, v65
	v_pk_mul_f32 v[56:57], v[60:61], v[56:57]
	v_pk_mul_f32 v[54:55], v[54:55], v[72:73]
	v_pk_mul_f32 v[56:57], v[56:57], v[64:65]
	v_cvt_pk_bf16_f32 v54, v54, v55
	v_cvt_pk_bf16_f32 v55, v56, v57
	global_store_dwordx2 v[62:63], v[54:55], off offset:64
	v_mov_b32_e32 v54, v144
	v_mov_b32_e32 v55, v145
	v_mov_b32_e32 v56, v146
	v_mov_b32_e32 v57, v147
	v_lshlrev_b32_e32 v58, 16, v70
	v_and_b32_e32 v59, 0xffff0000, v70
	v_lshlrev_b32_e32 v60, 16, v71
	v_and_b32_e32 v61, 0xffff0000, v71
	v_pk_mul_f32 v[50:51], v[50:51], v[54:55]
	v_pk_mul_f32 v[52:53], v[52:53], v[56:57]
	v_pk_mul_f32 v[50:51], v[50:51], v[58:59]
	v_pk_mul_f32 v[52:53], v[52:53], v[60:61]
	v_cvt_pk_bf16_f32 v50, v50, v51
	v_cvt_pk_bf16_f32 v51, v52, v53
	global_store_dwordx2 v[62:63], v[50:51], off offset:96
	v_mov_b32_e32 v50, v148
	v_mov_b32_e32 v51, v149
	v_mov_b32_e32 v52, v150
	v_mov_b32_e32 v53, v151
	s_nop 0
	v_mov_b32_e32 v54, v90
	v_mov_b32_e32 v55, v91
	v_pk_mul_f32 v[46:47], v[46:47], v[0:1] op_sel_hi:[1,0]
	v_pk_mul_f32 v[48:49], v[48:49], v[0:1] op_sel_hi:[1,0]
	v_pk_mul_f32 v[42:43], v[42:43], v[0:1] op_sel_hi:[1,0]
	v_pk_mul_f32 v[44:45], v[44:45], v[0:1] op_sel_hi:[1,0]
	v_pk_mul_f32 v[38:39], v[38:39], v[0:1] op_sel_hi:[1,0]
	v_pk_mul_f32 v[40:41], v[40:41], v[0:1] op_sel_hi:[1,0]
	v_pk_mul_f32 v[34:35], v[34:35], v[0:1] op_sel_hi:[1,0]
	v_pk_mul_f32 v[36:37], v[36:37], v[0:1] op_sel_hi:[1,0]
	v_pk_mul_f32 v[46:47], v[46:47], v[50:51]
	v_lshlrev_b32_e32 v50, 16, v54
	v_and_b32_e32 v51, 0xffff0000, v54
	v_pk_mul_f32 v[46:47], v[46:47], v[50:51]
	v_pk_mul_f32 v[48:49], v[48:49], v[52:53]
	v_lshlrev_b32_e32 v50, 16, v55
	v_and_b32_e32 v51, 0xffff0000, v55
	v_pk_mul_f32 v[48:49], v[48:49], v[50:51]
	v_cvt_pk_bf16_f32 v46, v46, v47
	v_cvt_pk_bf16_f32 v47, v48, v49
	global_store_dwordx2 v[62:63], v[46:47], off offset:128
	v_mov_b32_e32 v46, v152
	v_mov_b32_e32 v47, v153
	v_mov_b32_e32 v48, v154
	v_mov_b32_e32 v49, v155
	s_nop 0
	v_mov_b32_e32 v50, v92
	v_mov_b32_e32 v51, v93
	v_pk_mul_f32 v[42:43], v[42:43], v[46:47]
	v_lshlrev_b32_e32 v46, 16, v50
	v_and_b32_e32 v47, 0xffff0000, v50
	v_pk_mul_f32 v[42:43], v[42:43], v[46:47]
	v_pk_mul_f32 v[44:45], v[44:45], v[48:49]
	v_lshlrev_b32_e32 v46, 16, v51
	v_and_b32_e32 v47, 0xffff0000, v51
	v_pk_mul_f32 v[44:45], v[44:45], v[46:47]
	v_cvt_pk_bf16_f32 v42, v42, v43
	v_cvt_pk_bf16_f32 v43, v44, v45
	global_store_dwordx2 v[62:63], v[42:43], off offset:160
	v_mov_b32_e32 v42, v156
	v_mov_b32_e32 v43, v157
	v_mov_b32_e32 v44, v158
	v_mov_b32_e32 v45, v159
	s_nop 0
	v_mov_b32_e32 v46, v94
	v_mov_b32_e32 v47, v95
	v_pk_mul_f32 v[38:39], v[38:39], v[42:43]
	v_lshlrev_b32_e32 v42, 16, v46
	v_and_b32_e32 v43, 0xffff0000, v46
	v_pk_mul_f32 v[38:39], v[38:39], v[42:43]
	v_pk_mul_f32 v[40:41], v[40:41], v[44:45]
	v_lshlrev_b32_e32 v42, 16, v47
	v_and_b32_e32 v43, 0xffff0000, v47
	v_pk_mul_f32 v[40:41], v[40:41], v[42:43]
	v_cvt_pk_bf16_f32 v38, v38, v39
	v_cvt_pk_bf16_f32 v39, v40, v41
	global_store_dwordx2 v[62:63], v[38:39], off offset:192
	v_mov_b32_e32 v38, v160
	v_mov_b32_e32 v39, v161
	v_mov_b32_e32 v40, v162
	v_mov_b32_e32 v41, v163
	s_nop 0
	v_mov_b32_e32 v42, v96
	v_mov_b32_e32 v43, v97
	v_pk_mul_f32 v[34:35], v[34:35], v[38:39]
	v_lshlrev_b32_e32 v38, 16, v42
	v_and_b32_e32 v39, 0xffff0000, v42
	v_pk_mul_f32 v[34:35], v[34:35], v[38:39]
	v_pk_mul_f32 v[36:37], v[36:37], v[40:41]
	v_lshlrev_b32_e32 v38, 16, v43
	v_and_b32_e32 v39, 0xffff0000, v43
	v_pk_mul_f32 v[36:37], v[36:37], v[38:39]
	v_cvt_pk_bf16_f32 v34, v34, v35
	v_cvt_pk_bf16_f32 v35, v36, v37
	global_store_dwordx2 v[62:63], v[34:35], off offset:224
	v_mov_b32_e32 v34, v172
	v_mov_b32_e32 v35, v173
	v_mov_b32_e32 v36, v174
	v_mov_b32_e32 v37, v175
	s_nop 0
	v_mov_b32_e32 v38, v102
	v_mov_b32_e32 v39, v103
	v_pk_mul_f32 v[30:31], v[30:31], v[0:1] op_sel_hi:[1,0]
	v_pk_mul_f32 v[32:33], v[32:33], v[0:1] op_sel_hi:[1,0]
	v_pk_mul_f32 v[26:27], v[26:27], v[0:1] op_sel_hi:[1,0]
	v_pk_mul_f32 v[28:29], v[28:29], v[0:1] op_sel_hi:[1,0]
	v_pk_mul_f32 v[22:23], v[22:23], v[0:1] op_sel_hi:[1,0]
	v_pk_mul_f32 v[24:25], v[24:25], v[0:1] op_sel_hi:[1,0]
	v_pk_mul_f32 v[18:19], v[18:19], v[0:1] op_sel_hi:[1,0]
	v_pk_mul_f32 v[20:21], v[20:21], v[0:1] op_sel_hi:[1,0]
	v_pk_mul_f32 v[30:31], v[30:31], v[34:35]
	v_lshlrev_b32_e32 v34, 16, v38
	v_and_b32_e32 v35, 0xffff0000, v38
	v_pk_mul_f32 v[30:31], v[30:31], v[34:35]
	v_pk_mul_f32 v[32:33], v[32:33], v[36:37]
	v_lshlrev_b32_e32 v34, 16, v39
	v_and_b32_e32 v35, 0xffff0000, v39
	v_pk_mul_f32 v[32:33], v[32:33], v[34:35]
	v_cvt_pk_bf16_f32 v30, v30, v31
	v_cvt_pk_bf16_f32 v31, v32, v33
	global_store_dwordx2 v[62:63], v[30:31], off offset:256
	v_mov_b32_e32 v30, v176
	v_mov_b32_e32 v31, v177
	v_mov_b32_e32 v32, v178
	v_mov_b32_e32 v33, v179
	s_nop 0
	v_mov_b32_e32 v34, v104
	v_mov_b32_e32 v35, v105
	v_pk_mul_f32 v[26:27], v[26:27], v[30:31]
	v_lshlrev_b32_e32 v30, 16, v34
	v_and_b32_e32 v31, 0xffff0000, v34
	v_pk_mul_f32 v[26:27], v[26:27], v[30:31]
	v_pk_mul_f32 v[28:29], v[28:29], v[32:33]
	v_lshlrev_b32_e32 v30, 16, v35
	v_and_b32_e32 v31, 0xffff0000, v35
	v_pk_mul_f32 v[28:29], v[28:29], v[30:31]
	v_cvt_pk_bf16_f32 v26, v26, v27
	v_cvt_pk_bf16_f32 v27, v28, v29
	global_store_dwordx2 v[62:63], v[26:27], off offset:288
	v_mov_b32_e32 v26, v180
	v_mov_b32_e32 v27, v181
	v_mov_b32_e32 v28, v182
	v_mov_b32_e32 v29, v183
	s_nop 0
	v_mov_b32_e32 v30, v106
	v_mov_b32_e32 v31, v107
	v_pk_mul_f32 v[22:23], v[22:23], v[26:27]
	v_lshlrev_b32_e32 v26, 16, v30
	v_and_b32_e32 v27, 0xffff0000, v30
	v_pk_mul_f32 v[22:23], v[22:23], v[26:27]
	v_pk_mul_f32 v[24:25], v[24:25], v[28:29]
	v_lshlrev_b32_e32 v26, 16, v31
	v_and_b32_e32 v27, 0xffff0000, v31
	v_pk_mul_f32 v[24:25], v[24:25], v[26:27]
	v_cvt_pk_bf16_f32 v22, v22, v23
	v_cvt_pk_bf16_f32 v23, v24, v25
	global_store_dwordx2 v[62:63], v[22:23], off offset:320
	v_mov_b32_e32 v22, v184
	v_mov_b32_e32 v23, v185
	v_mov_b32_e32 v24, v186
	v_mov_b32_e32 v25, v187
	s_nop 0
	v_mov_b32_e32 v26, v108
	v_mov_b32_e32 v27, v109
	v_pk_mul_f32 v[18:19], v[18:19], v[22:23]
	v_lshlrev_b32_e32 v22, 16, v26
	v_and_b32_e32 v23, 0xffff0000, v26
	v_pk_mul_f32 v[18:19], v[18:19], v[22:23]
	v_pk_mul_f32 v[20:21], v[20:21], v[24:25]
	v_lshlrev_b32_e32 v22, 16, v27
	v_and_b32_e32 v23, 0xffff0000, v27
	v_pk_mul_f32 v[20:21], v[20:21], v[22:23]
	v_cvt_pk_bf16_f32 v18, v18, v19
	v_cvt_pk_bf16_f32 v19, v20, v21
	global_store_dwordx2 v[62:63], v[18:19], off offset:352
	v_mov_b32_e32 v18, v188
	v_mov_b32_e32 v19, v189
	v_mov_b32_e32 v20, v190
	v_mov_b32_e32 v21, v191
	s_nop 0
	v_mov_b32_e32 v22, v110
	v_mov_b32_e32 v23, v111
	v_pk_mul_f32 v[14:15], v[14:15], v[0:1] op_sel_hi:[1,0]
	v_pk_mul_f32 v[16:17], v[16:17], v[0:1] op_sel_hi:[1,0]
	v_pk_mul_f32 v[10:11], v[10:11], v[0:1] op_sel_hi:[1,0]
	v_pk_mul_f32 v[12:13], v[12:13], v[0:1] op_sel_hi:[1,0]
	v_pk_mul_f32 v[6:7], v[6:7], v[0:1] op_sel_hi:[1,0]
	v_pk_mul_f32 v[8:9], v[8:9], v[0:1] op_sel_hi:[1,0]
	v_readlane_b32 s3, v255, 59
	v_readlane_b32 s2, v254, 7
	v_readlane_b32 s12, v255, 61
	v_pk_mul_f32 v[2:3], v[2:3], v[0:1] op_sel_hi:[1,0]
	s_add_i32 s8, s3, 1
	s_add_i32 s12, s12, s2
	v_pk_mul_f32 v[4:5], v[4:5], v[0:1] op_sel_hi:[1,0]
	s_cmp_eq_u32 s3, 0
	v_readlane_b32 s6, v255, 30
	s_cselect_b64 s[2:3], -1, 0
	v_readlane_b32 s7, v255, 31
	s_and_b64 s[2:3], s[6:7], s[2:3]
	s_cmpk_lt_i32 s12, 0x180
	s_cselect_b64 s[6:7], -1, 0
	v_cndmask_b32_e64 v0, 0, 1, s[6:7]
	v_pk_mul_f32 v[14:15], v[14:15], v[18:19]
	v_lshlrev_b32_e32 v18, 16, v22
	v_and_b32_e32 v19, 0xffff0000, v22
	v_pk_mul_f32 v[14:15], v[14:15], v[18:19]
	v_pk_mul_f32 v[16:17], v[16:17], v[20:21]
	v_lshlrev_b32_e32 v18, 16, v23
	v_and_b32_e32 v19, 0xffff0000, v23
	v_pk_mul_f32 v[16:17], v[16:17], v[18:19]
	v_cvt_pk_bf16_f32 v14, v14, v15
	v_cvt_pk_bf16_f32 v15, v16, v17
	global_store_dwordx2 v[62:63], v[14:15], off offset:384
	v_mov_b32_e32 v14, v192
	v_mov_b32_e32 v15, v193
	v_mov_b32_e32 v16, v194
	v_mov_b32_e32 v17, v195
	s_nop 0
	v_mov_b32_e32 v18, v112
	v_mov_b32_e32 v19, v113
	v_pk_mul_f32 v[10:11], v[10:11], v[14:15]
	v_lshlrev_b32_e32 v14, 16, v18
	v_and_b32_e32 v15, 0xffff0000, v18
	v_pk_mul_f32 v[10:11], v[10:11], v[14:15]
	v_pk_mul_f32 v[12:13], v[12:13], v[16:17]
	v_lshlrev_b32_e32 v14, 16, v19
	v_and_b32_e32 v15, 0xffff0000, v19
	v_pk_mul_f32 v[12:13], v[12:13], v[14:15]
	v_cvt_pk_bf16_f32 v10, v10, v11
	v_cvt_pk_bf16_f32 v11, v12, v13
	global_store_dwordx2 v[62:63], v[10:11], off offset:416
	v_mov_b32_e32 v10, v196
	v_mov_b32_e32 v11, v197
	v_mov_b32_e32 v12, v198
	v_mov_b32_e32 v13, v199
	s_nop 0
	v_mov_b32_e32 v14, v120
	v_mov_b32_e32 v15, v121
	v_pk_mul_f32 v[6:7], v[6:7], v[10:11]
	v_lshlrev_b32_e32 v10, 16, v14
	v_and_b32_e32 v11, 0xffff0000, v14
	v_pk_mul_f32 v[6:7], v[6:7], v[10:11]
	v_pk_mul_f32 v[8:9], v[8:9], v[12:13]
	v_lshlrev_b32_e32 v10, 16, v15
	v_and_b32_e32 v11, 0xffff0000, v15
	v_pk_mul_f32 v[8:9], v[8:9], v[10:11]
	v_cvt_pk_bf16_f32 v6, v6, v7
	v_cvt_pk_bf16_f32 v7, v8, v9
	global_store_dwordx2 v[62:63], v[6:7], off offset:448
	v_mov_b32_e32 v6, v204
	v_mov_b32_e32 v7, v205
	v_mov_b32_e32 v8, v206
	v_mov_b32_e32 v9, v207
	s_nop 0
	v_mov_b32_e32 v10, v122
	v_mov_b32_e32 v11, v123
	v_pk_mul_f32 v[2:3], v[2:3], v[6:7]
	v_lshlrev_b32_e32 v6, 16, v10
	v_and_b32_e32 v7, 0xffff0000, v10
	v_pk_mul_f32 v[2:3], v[2:3], v[6:7]
	v_pk_mul_f32 v[4:5], v[4:5], v[8:9]
	v_lshlrev_b32_e32 v6, 16, v11
	v_and_b32_e32 v7, 0xffff0000, v11
	v_pk_mul_f32 v[4:5], v[4:5], v[6:7]
	v_cvt_pk_bf16_f32 v2, v2, v3
	v_cvt_pk_bf16_f32 v3, v4, v5
	global_store_dwordx2 v[62:63], v[2:3], off offset:480
	v_cndmask_b32_e64 v2, 0, 1, s[2:3]
	v_readlane_b32 s2, v254, 5
	v_readlane_b32 s3, v254, 6
	s_nop 1
	v_cndmask_b32_e64 v0, v0, v2, s[2:3]
	v_and_b32_e32 v0, 1, v0
	v_cmp_eq_u32_e32 vcc, 0, v0
	s_cbranch_vccnz .LBB0_273
